# P6 sample rows: the 32 serialized partial-sum loads batched 8 at a time, two groups in flight
# baseline (speedup 1.0000x reference)
.LBB0_701:
	s_andn2_b64 vcc, exec, s[4:5]
	s_add_i32 s4, s24, 0xffff8000
	s_cbranch_vccnz .LBB0_703
	s_mov_b32 s5, s25
	s_lshl_b64 s[56:57], s[4:5], 13
	v_lshl_add_u64 v[150:151], v[98:99], 0, s[56:57]
	v_add_co_u32_e32 v172, vcc, s30, v150
	s_nop 1
	v_addc_co_u32_e32 v173, vcc, 0, v151, vcc
	v_add_co_u32_e32 v174, vcc, s35, v150
	s_nop 1
	v_addc_co_u32_e32 v175, vcc, 0, v151, vcc
	v_add_co_u32_e32 v176, vcc, s63, v150
	s_nop 1
	v_addc_co_u32_e32 v177, vcc, 0, v151, vcc
	v_add_co_u32_e32 v178, vcc, s65, v150
	s_nop 1
	v_addc_co_u32_e32 v179, vcc, 0, v151, vcc
	global_load_dwordx4 v[204:207], v[172:173], off offset:-4096
	global_load_dwordx4 v[208:211], v[172:173], off offset:-3072
	global_load_dwordx4 v[212:215], v[172:173], off offset:-2048
	global_load_dwordx4 v[216:219], v[172:173], off offset:-1024
	global_load_dwordx4 v[220:223], v[172:173], off
	global_load_dwordx4 v[224:227], v[172:173], off offset:1024
	global_load_dwordx4 v[228:231], v[172:173], off offset:2048
	global_load_dwordx4 v[232:235], v[172:173], off offset:3072
	global_load_dwordx4 v[180:183], v[174:175], off offset:-4096
	global_load_dwordx4 v[184:187], v[174:175], off offset:-3072
	global_load_dwordx4 v[188:191], v[174:175], off offset:-2048
	global_load_dwordx4 v[192:195], v[174:175], off offset:-1024
	global_load_dwordx4 v[196:199], v[174:175], off
	global_load_dwordx4 v[236:239], v[174:175], off offset:1024
	global_load_dwordx4 v[240:243], v[174:175], off offset:2048
	global_load_dwordx4 v[244:247], v[174:175], off offset:3072
	s_waitcnt vmcnt(8)
	v_pk_add_f32 v[92:93], v[92:93], v[204:205]
	v_pk_add_f32 v[94:95], v[94:95], v[206:207]
	v_pk_add_f32 v[88:89], v[88:89], v[208:209]
	v_pk_add_f32 v[90:91], v[90:91], v[210:211]
	v_pk_add_f32 v[82:83], v[82:83], v[212:213]
	v_pk_add_f32 v[84:85], v[84:85], v[214:215]
	v_pk_add_f32 v[76:77], v[76:77], v[216:217]
	v_pk_add_f32 v[78:79], v[78:79], v[218:219]
	v_pk_add_f32 v[72:73], v[72:73], v[220:221]
	v_pk_add_f32 v[74:75], v[74:75], v[222:223]
	v_pk_add_f32 v[68:69], v[68:69], v[224:225]
	v_pk_add_f32 v[70:71], v[70:71], v[226:227]
	v_pk_add_f32 v[64:65], v[64:65], v[228:229]
	v_pk_add_f32 v[66:67], v[66:67], v[230:231]
	v_pk_add_f32 v[86:87], v[86:87], v[232:233]
	v_pk_add_f32 v[80:81], v[80:81], v[234:235]
	global_load_dwordx4 v[204:207], v[176:177], off offset:-4096
	global_load_dwordx4 v[208:211], v[176:177], off offset:-3072
	global_load_dwordx4 v[212:215], v[176:177], off offset:-2048
	global_load_dwordx4 v[216:219], v[176:177], off offset:-1024
	global_load_dwordx4 v[220:223], v[176:177], off
	global_load_dwordx4 v[224:227], v[176:177], off offset:1024
	global_load_dwordx4 v[228:231], v[176:177], off offset:2048
	global_load_dwordx4 v[232:235], v[176:177], off offset:3072
	s_waitcnt vmcnt(8)
	v_pk_add_f32 v[92:93], v[92:93], v[180:181]
	v_pk_add_f32 v[94:95], v[94:95], v[182:183]
	v_pk_add_f32 v[88:89], v[88:89], v[184:185]
	v_pk_add_f32 v[90:91], v[90:91], v[186:187]
	v_pk_add_f32 v[82:83], v[82:83], v[188:189]
	v_pk_add_f32 v[84:85], v[84:85], v[190:191]
	v_pk_add_f32 v[76:77], v[76:77], v[192:193]
	v_pk_add_f32 v[78:79], v[78:79], v[194:195]
	v_pk_add_f32 v[72:73], v[72:73], v[196:197]
	v_pk_add_f32 v[74:75], v[74:75], v[198:199]
	v_pk_add_f32 v[68:69], v[68:69], v[236:237]
	v_pk_add_f32 v[70:71], v[70:71], v[238:239]
	v_pk_add_f32 v[64:65], v[64:65], v[240:241]
	v_pk_add_f32 v[66:67], v[66:67], v[242:243]
	v_pk_add_f32 v[86:87], v[86:87], v[244:245]
	v_pk_add_f32 v[80:81], v[80:81], v[246:247]
	global_load_dwordx4 v[180:183], v[178:179], off offset:-4096
	global_load_dwordx4 v[184:187], v[178:179], off offset:-3072
	global_load_dwordx4 v[188:191], v[178:179], off offset:-2048
	global_load_dwordx4 v[192:195], v[178:179], off offset:-1024
	global_load_dwordx4 v[196:199], v[178:179], off
	global_load_dwordx4 v[236:239], v[178:179], off offset:1024
	global_load_dwordx4 v[240:243], v[178:179], off offset:2048
	global_load_dwordx4 v[244:247], v[178:179], off offset:3072
	s_waitcnt vmcnt(8)
	v_pk_add_f32 v[92:93], v[92:93], v[204:205]
	v_pk_add_f32 v[94:95], v[94:95], v[206:207]
	v_pk_add_f32 v[88:89], v[88:89], v[208:209]
	v_pk_add_f32 v[90:91], v[90:91], v[210:211]
	v_pk_add_f32 v[82:83], v[82:83], v[212:213]
	v_pk_add_f32 v[84:85], v[84:85], v[214:215]
	v_pk_add_f32 v[76:77], v[76:77], v[216:217]
	v_pk_add_f32 v[78:79], v[78:79], v[218:219]
	v_pk_add_f32 v[72:73], v[72:73], v[220:221]
	v_pk_add_f32 v[74:75], v[74:75], v[222:223]
	v_pk_add_f32 v[68:69], v[68:69], v[224:225]
	v_pk_add_f32 v[70:71], v[70:71], v[226:227]
	v_pk_add_f32 v[64:65], v[64:65], v[228:229]
	v_pk_add_f32 v[66:67], v[66:67], v[230:231]
	v_pk_add_f32 v[86:87], v[86:87], v[232:233]
	v_pk_add_f32 v[80:81], v[80:81], v[234:235]
	s_waitcnt vmcnt(0)
	v_pk_add_f32 v[92:93], v[92:93], v[180:181]
	v_pk_add_f32 v[94:95], v[94:95], v[182:183]
	v_pk_add_f32 v[88:89], v[88:89], v[184:185]
	v_pk_add_f32 v[90:91], v[90:91], v[186:187]
	v_pk_add_f32 v[82:83], v[82:83], v[188:189]
	v_pk_add_f32 v[84:85], v[84:85], v[190:191]
	v_pk_add_f32 v[76:77], v[76:77], v[192:193]
	v_pk_add_f32 v[78:79], v[78:79], v[194:195]
	v_pk_add_f32 v[72:73], v[72:73], v[196:197]
	v_pk_add_f32 v[74:75], v[74:75], v[198:199]
	v_pk_add_f32 v[68:69], v[68:69], v[236:237]
	v_pk_add_f32 v[70:71], v[70:71], v[238:239]
	v_pk_add_f32 v[64:65], v[64:65], v[240:241]
	v_pk_add_f32 v[66:67], v[66:67], v[242:243]
	v_pk_add_f32 v[86:87], v[86:87], v[244:245]
	v_pk_add_f32 v[80:81], v[80:81], v[246:247]
	v_lshl_add_u64 v[150:151], s[54:55], 1, v[100:101]
	v_cvt_pk_bf16_f32 v152, v92, v93
	v_cvt_pk_bf16_f32 v153, v94, v95
	global_store_dwordx2 v[150:151], v[152:153], off
	v_cvt_pk_bf16_f32 v152, v88, v89
	v_cvt_pk_bf16_f32 v153, v90, v91
	global_store_dwordx2 v[150:151], v[152:153], off offset:512
	v_cvt_pk_bf16_f32 v152, v82, v83
	v_cvt_pk_bf16_f32 v153, v84, v85
	global_store_dwordx2 v[150:151], v[152:153], off offset:1024
	v_cvt_pk_bf16_f32 v152, v76, v77
	v_cvt_pk_bf16_f32 v153, v78, v79
	global_store_dwordx2 v[150:151], v[152:153], off offset:1536
	v_cvt_pk_bf16_f32 v152, v72, v73
	v_cvt_pk_bf16_f32 v153, v74, v75
	global_store_dwordx2 v[150:151], v[152:153], off offset:2048
	v_cvt_pk_bf16_f32 v152, v68, v69
	v_cvt_pk_bf16_f32 v153, v70, v71
	global_store_dwordx2 v[150:151], v[152:153], off offset:2560
	v_cvt_pk_bf16_f32 v152, v64, v65
	v_cvt_pk_bf16_f32 v153, v66, v67
	global_store_dwordx2 v[150:151], v[152:153], off offset:3072
	v_cvt_pk_bf16_f32 v152, v86, v87
	v_cvt_pk_bf16_f32 v153, v80, v81
	global_store_dwordx2 v[150:151], v[152:153], off offset:3584
